# P6 loop: rebalance LDS-DMA issue 4/4 between the two load segments (waits 8/6) on top of E3
# speedup vs baseline: 1.0066x; 1.0066x over previous
.LBB0_1040:
	v_lshrrev_b32_e32 v12, 1, v10
	v_and_b32_e32 v12, 24, v12
	s_add_u32 s18, s26, 0x22200000
	v_and_b32_e32 v11, 15, v10
	v_lshlrev_b32_e32 v13, 1, v12
	v_lshlrev_b32_e32 v10, 2, v10
	s_addc_u32 s19, s27, 0
	v_lshl_or_b32 v141, s0, 6, v11
	v_lshl_or_b32 v11, v11, 6, v13
	s_lshl_b32 s0, s0, 13
	v_and_b32_e32 v10, 32, v10
	v_bitop3_b32 v13, v11, s0, v10 bitop3:0xde
	s_lshl_b32 s0, s1, 5
	s_and_b32 s2, s0, 0x60
	s_add_i32 m0, s95, 0x18000
	v_lshl_add_u64 v[8:9], v[8:9], 0, s[42:43]
	s_lshl_b32 s0, s2, 7
	s_waitcnt vmcnt(2)
	s_barrier
	global_load_lds_dwordx4 v[8:9], off
	v_lshl_add_u64 v[6:7], v[6:7], 0, s[42:43]
	s_add_i32 m0, s95, 0x1a000
	s_add_i32 s30, s95, 0x8000
	s_add_i32 s31, s95, 0xa000
	v_bitop3_b32 v142, v11, s0, v10 bitop3:0xde
	global_load_lds_dwordx4 v[6:7], off
	v_lshl_add_u64 v[2:3], v[2:3], 0, s[42:43]
	s_mov_b32 m0, s30
	s_add_u32 s0, s86, 0x80080
	v_lshl_add_u64 v[2:3], v[4:5], 0, s[42:43]
	s_mov_b32 m0, s31
	s_addc_u32 s1, s87, 0
	s_add_i32 m0, s95, 0x1c000
	v_lshl_add_u64 v[2:3], s[0:1], 0, v[202:203]
	global_load_lds_dwordx4 v[2:3], off
	v_lshl_add_u64 v[2:3], s[0:1], 0, v[134:135]
	s_add_i32 m0, s95, 0x1e000
	s_cmpk_lt_u32 s20, 0x100
	global_load_lds_dwordx4 v[2:3], off
	s_waitcnt vmcnt(4)
	s_cselect_b64 s[20:21], -1, 0
	s_lshr_b32 s54, s68, 3
	v_or_b32_e32 v143, s2, v12
	s_mov_b32 s56, 0
	v_add_u32_e32 v144, 0, v13
	s_barrier
	s_branch .LBB0_1043

.LBB0_1049:
	s_or_b32 s22, s88, 1
	s_lshl_b64 s[0:1], s[22:23], 7
	s_add_u32 s38, s6, s0
	s_addc_u32 s39, s7, s1
	s_add_i32 s22, s88, 2
	s_lshl_b64 s[0:1], s[22:23], 7
	s_add_u32 s62, s6, s0
	s_addc_u32 s63, s7, s1
	s_and_b64 s[2:3], s[28:29], exec
	s_cselect_b32 s3, s63, s77
	s_cselect_b32 s2, s62, s58
	s_add_u32 s62, s86, s0
	s_addc_u32 s63, s87, s1
	s_and_b64 s[0:1], s[28:29], exec
	s_cselect_b32 s29, s63, s93
	s_cselect_b32 s28, s62, s89
	s_add_i32 s62, 0, 0x10000
	v_add_u32_e32 v145, s62, v142
	s_add_i32 s63, 0, 0x14000
	ds_read_b128 v[136:139], v145
	ds_read_b128 v[146:149], v145 offset:1024
	ds_read_b128 v[150:153], v145 offset:2048
	ds_read_b128 v[154:157], v145 offset:3072
	v_add_u32_e32 v145, s63, v142
	ds_read_b128 v[158:161], v145
	ds_read_b128 v[162:165], v145 offset:1024
	ds_read_b128 v[166:169], v145 offset:2048
	ds_read_b128 v[170:173], v145 offset:3072
	s_add_u32 s0, s38, 0x80000
	s_addc_u32 s1, s39, 0
	s_mov_b32 m0, s30
	s_nop 0
	global_load_lds_dwordx4 v130, s[38:39]
	s_mov_b32 m0, s31
	s_nop 0
	global_load_lds_dwordx4 v132, s[38:39]
	s_add_i32 m0, s95, 0xc000
	ds_read_b128 v[174:177], v144
	ds_read_b128 v[178:181], v144 offset:1024
	ds_read_b128 v[182:185], v144 offset:2048
	ds_read_b128 v[186:189], v144 offset:3072
	ds_read_b128 v[190:193], v144 offset:4096
	ds_read_b128 v[194:197], v144 offset:5120
	ds_read_b128 v[198:201], v144 offset:6144
	ds_read_b128 v[226:229], v144 offset:7168
	global_load_lds_dwordx4 v130, s[0:1]
	s_add_i32 m0, s95, 0xe000
	s_nop 0
	global_load_lds_dwordx4 v132, s[0:1]
	s_waitcnt vmcnt(8)
	s_waitcnt lgkmcnt(0)
	s_barrier
	s_setprio 1
	v_mfma_f32_16x16x32_bf16 v[126:129], v[136:139], v[174:177], v[126:129]
	v_mfma_f32_16x16x32_bf16 v[114:117], v[150:153], v[174:177], v[114:117]
	v_mfma_f32_16x16x32_bf16 v[110:113], v[136:139], v[182:185], v[110:113]
	v_mfma_f32_16x16x32_bf16 v[98:101], v[150:153], v[182:185], v[98:101]
	v_mfma_f32_16x16x32_bf16 v[94:97], v[136:139], v[190:193], v[94:97]
	v_mfma_f32_16x16x32_bf16 v[82:85], v[150:153], v[190:193], v[82:85]
	v_mfma_f32_16x16x32_bf16 v[78:81], v[136:139], v[198:201], v[78:81]
	v_mfma_f32_16x16x32_bf16 v[66:69], v[150:153], v[198:201], v[66:69]
	v_mfma_f32_16x16x32_bf16 v[126:129], v[146:149], v[178:181], v[126:129]
	v_mfma_f32_16x16x32_bf16 v[114:117], v[154:157], v[178:181], v[114:117]
	v_mfma_f32_16x16x32_bf16 v[110:113], v[146:149], v[186:189], v[110:113]
	v_mfma_f32_16x16x32_bf16 v[98:101], v[154:157], v[186:189], v[98:101]
	v_mfma_f32_16x16x32_bf16 v[94:97], v[146:149], v[194:197], v[94:97]
	v_mfma_f32_16x16x32_bf16 v[82:85], v[154:157], v[194:197], v[82:85]
	v_mfma_f32_16x16x32_bf16 v[78:81], v[146:149], v[226:229], v[78:81]
	v_mfma_f32_16x16x32_bf16 v[66:69], v[154:157], v[226:229], v[66:69]
	v_mfma_f32_16x16x32_bf16 v[122:125], v[158:161], v[174:177], v[122:125]
	v_mfma_f32_16x16x32_bf16 v[118:121], v[166:169], v[174:177], v[118:121]
	v_mfma_f32_16x16x32_bf16 v[106:109], v[158:161], v[182:185], v[106:109]
	v_mfma_f32_16x16x32_bf16 v[102:105], v[166:169], v[182:185], v[102:105]
	v_mfma_f32_16x16x32_bf16 v[90:93], v[158:161], v[190:193], v[90:93]
	v_mfma_f32_16x16x32_bf16 v[86:89], v[166:169], v[190:193], v[86:89]
	v_mfma_f32_16x16x32_bf16 v[74:77], v[158:161], v[198:201], v[74:77]
	v_mfma_f32_16x16x32_bf16 v[70:73], v[166:169], v[198:201], v[70:73]
	v_mfma_f32_16x16x32_bf16 v[122:125], v[162:165], v[178:181], v[122:125]
	v_mfma_f32_16x16x32_bf16 v[118:121], v[170:173], v[178:181], v[118:121]
	v_mfma_f32_16x16x32_bf16 v[106:109], v[162:165], v[186:189], v[106:109]
	v_mfma_f32_16x16x32_bf16 v[102:105], v[170:173], v[186:189], v[102:105]
	v_mfma_f32_16x16x32_bf16 v[90:93], v[162:165], v[194:197], v[90:93]
	v_mfma_f32_16x16x32_bf16 v[86:89], v[170:173], v[194:197], v[86:89]
	v_mfma_f32_16x16x32_bf16 v[74:77], v[162:165], v[226:229], v[74:77]
	v_mfma_f32_16x16x32_bf16 v[70:73], v[170:173], v[226:229], v[70:73]
	s_setprio 0
	s_barrier
	s_add_i32 s0, s62, s75
	v_lshl_add_u64 v[206:207], s[28:29], 0, v[202:203]
	s_mov_b32 m0, s0
	ds_read_b128 v[174:177], v144 offset:16384
	ds_read_b128 v[178:181], v144 offset:17408
	ds_read_b128 v[182:185], v144 offset:18432
	ds_read_b128 v[186:189], v144 offset:19456
	ds_read_b128 v[190:193], v144 offset:20480
	ds_read_b128 v[194:197], v144 offset:21504
	ds_read_b128 v[198:201], v144 offset:22528
	ds_read_b128 v[226:229], v144 offset:23552
	global_load_lds_dwordx4 v[206:207], off
	s_add_i32 m0, s0, 0x2000
	s_add_u32 s0, s28, 0x80000
	v_lshl_add_u64 v[230:231], s[28:29], 0, v[134:135]
	s_addc_u32 s1, s29, 0
	s_add_i32 s38, s63, s75
	global_load_lds_dwordx4 v[230:231], off
	v_lshl_add_u64 v[232:233], s[0:1], 0, v[202:203]
	s_mov_b32 m0, s38
	s_nop 0
	global_load_lds_dwordx4 v[232:233], off
	v_lshl_add_u64 v[232:233], s[0:1], 0, v[134:135]
	s_add_i32 m0, s38, 0x2000
	s_nop 0
	global_load_lds_dwordx4 v[232:233], off
	s_waitcnt vmcnt(6)
	s_waitcnt lgkmcnt(0)
	s_barrier
	s_setprio 1
	v_mfma_f32_16x16x32_bf16 v[62:65], v[136:139], v[174:177], v[62:65]
	v_mfma_f32_16x16x32_bf16 v[50:53], v[150:153], v[174:177], v[50:53]
	v_mfma_f32_16x16x32_bf16 v[46:49], v[136:139], v[182:185], v[46:49]
	v_mfma_f32_16x16x32_bf16 v[34:37], v[150:153], v[182:185], v[34:37]
	v_mfma_f32_16x16x32_bf16 v[30:33], v[136:139], v[190:193], v[30:33]
	v_mfma_f32_16x16x32_bf16 v[18:21], v[150:153], v[190:193], v[18:21]
	v_mfma_f32_16x16x32_bf16 v[14:17], v[136:139], v[198:201], v[14:17]
	v_mfma_f32_16x16x32_bf16 v[6:9], v[150:153], v[198:201], v[6:9]
	v_mfma_f32_16x16x32_bf16 v[62:65], v[146:149], v[178:181], v[62:65]
	v_mfma_f32_16x16x32_bf16 v[50:53], v[154:157], v[178:181], v[50:53]
	v_mfma_f32_16x16x32_bf16 v[46:49], v[146:149], v[186:189], v[46:49]
	v_mfma_f32_16x16x32_bf16 v[34:37], v[154:157], v[186:189], v[34:37]
	v_mfma_f32_16x16x32_bf16 v[30:33], v[146:149], v[194:197], v[30:33]
	v_mfma_f32_16x16x32_bf16 v[18:21], v[154:157], v[194:197], v[18:21]
	v_mfma_f32_16x16x32_bf16 v[14:17], v[146:149], v[226:229], v[14:17]
	v_mfma_f32_16x16x32_bf16 v[6:9], v[154:157], v[226:229], v[6:9]
	v_mfma_f32_16x16x32_bf16 v[58:61], v[158:161], v[174:177], v[58:61]
	v_mfma_f32_16x16x32_bf16 v[54:57], v[166:169], v[174:177], v[54:57]
	v_mfma_f32_16x16x32_bf16 v[42:45], v[158:161], v[182:185], v[42:45]
	v_mfma_f32_16x16x32_bf16 v[38:41], v[166:169], v[182:185], v[38:41]
	v_mfma_f32_16x16x32_bf16 v[26:29], v[158:161], v[190:193], v[26:29]
	v_mfma_f32_16x16x32_bf16 v[22:25], v[166:169], v[190:193], v[22:25]
	v_mfma_f32_16x16x32_bf16 v[10:13], v[158:161], v[198:201], v[10:13]
	v_mfma_f32_16x16x32_bf16 v[2:5], v[166:169], v[198:201], v[2:5]
	v_mfma_f32_16x16x32_bf16 v[58:61], v[162:165], v[178:181], v[58:61]
	v_mfma_f32_16x16x32_bf16 v[54:57], v[170:173], v[178:181], v[54:57]
	v_mfma_f32_16x16x32_bf16 v[42:45], v[162:165], v[186:189], v[42:45]
	v_mfma_f32_16x16x32_bf16 v[38:41], v[170:173], v[186:189], v[38:41]
	v_mfma_f32_16x16x32_bf16 v[26:29], v[162:165], v[194:197], v[26:29]
	v_mfma_f32_16x16x32_bf16 v[22:25], v[170:173], v[194:197], v[22:25]
	v_mfma_f32_16x16x32_bf16 v[10:13], v[162:165], v[226:229], v[10:13]
	v_mfma_f32_16x16x32_bf16 v[2:5], v[170:173], v[226:229], v[2:5]
	s_setprio 0
	s_barrier
	s_add_i32 s38, 0, 0x18000
	v_add_u32_e32 v145, s38, v142
	s_add_i32 s39, 0, 0x1c000
	ds_read_b128 v[136:139], v145
	ds_read_b128 v[146:149], v145 offset:1024
	ds_read_b128 v[150:153], v145 offset:2048
	ds_read_b128 v[154:157], v145 offset:3072
	v_add_u32_e32 v145, s39, v142
	ds_read_b128 v[158:161], v145
	ds_read_b128 v[162:165], v145 offset:1024
	ds_read_b128 v[166:169], v145 offset:2048
	ds_read_b128 v[170:173], v145 offset:3072
	s_add_u32 s0, s2, 0x80000
	s_addc_u32 s1, s3, 0
	s_mov_b32 m0, s95
	s_nop 0
	global_load_lds_dwordx4 v130, s[2:3]
	s_mov_b32 m0, s97
	s_nop 0
	global_load_lds_dwordx4 v132, s[2:3]
	s_mov_b32 m0, s46
	ds_read_b128 v[174:177], v144 offset:32768
	ds_read_b128 v[178:181], v144 offset:33792
	ds_read_b128 v[182:185], v144 offset:34816
	ds_read_b128 v[186:189], v144 offset:35840
	ds_read_b128 v[190:193], v144 offset:36864
	ds_read_b128 v[194:197], v144 offset:37888
	ds_read_b128 v[198:201], v144 offset:38912
	ds_read_b128 v[226:229], v144 offset:39936
	global_load_lds_dwordx4 v130, s[0:1]
	s_mov_b32 m0, s48
	s_nop 0
	global_load_lds_dwordx4 v132, s[0:1]
	s_waitcnt vmcnt(8)
	s_waitcnt lgkmcnt(0)
	s_barrier
	s_setprio 1
	v_mfma_f32_16x16x32_bf16 v[126:129], v[136:139], v[174:177], v[126:129]
	v_mfma_f32_16x16x32_bf16 v[114:117], v[150:153], v[174:177], v[114:117]
	v_mfma_f32_16x16x32_bf16 v[110:113], v[136:139], v[182:185], v[110:113]
	v_mfma_f32_16x16x32_bf16 v[98:101], v[150:153], v[182:185], v[98:101]
	v_mfma_f32_16x16x32_bf16 v[94:97], v[136:139], v[190:193], v[94:97]
	v_mfma_f32_16x16x32_bf16 v[82:85], v[150:153], v[190:193], v[82:85]
	v_mfma_f32_16x16x32_bf16 v[78:81], v[136:139], v[198:201], v[78:81]
	v_mfma_f32_16x16x32_bf16 v[66:69], v[150:153], v[198:201], v[66:69]
	v_mfma_f32_16x16x32_bf16 v[126:129], v[146:149], v[178:181], v[126:129]
	v_mfma_f32_16x16x32_bf16 v[114:117], v[154:157], v[178:181], v[114:117]
	v_mfma_f32_16x16x32_bf16 v[110:113], v[146:149], v[186:189], v[110:113]
	v_mfma_f32_16x16x32_bf16 v[98:101], v[154:157], v[186:189], v[98:101]
	v_mfma_f32_16x16x32_bf16 v[94:97], v[146:149], v[194:197], v[94:97]
	v_mfma_f32_16x16x32_bf16 v[82:85], v[154:157], v[194:197], v[82:85]
	v_mfma_f32_16x16x32_bf16 v[78:81], v[146:149], v[226:229], v[78:81]
	v_mfma_f32_16x16x32_bf16 v[66:69], v[154:157], v[226:229], v[66:69]
	v_mfma_f32_16x16x32_bf16 v[122:125], v[158:161], v[174:177], v[122:125]
	v_mfma_f32_16x16x32_bf16 v[118:121], v[166:169], v[174:177], v[118:121]
	v_mfma_f32_16x16x32_bf16 v[106:109], v[158:161], v[182:185], v[106:109]
	v_mfma_f32_16x16x32_bf16 v[102:105], v[166:169], v[182:185], v[102:105]
	v_mfma_f32_16x16x32_bf16 v[90:93], v[158:161], v[190:193], v[90:93]
	v_mfma_f32_16x16x32_bf16 v[86:89], v[166:169], v[190:193], v[86:89]
	v_mfma_f32_16x16x32_bf16 v[74:77], v[158:161], v[198:201], v[74:77]
	v_mfma_f32_16x16x32_bf16 v[70:73], v[166:169], v[198:201], v[70:73]
	v_mfma_f32_16x16x32_bf16 v[122:125], v[162:165], v[178:181], v[122:125]
	v_mfma_f32_16x16x32_bf16 v[118:121], v[170:173], v[178:181], v[118:121]
	v_mfma_f32_16x16x32_bf16 v[106:109], v[162:165], v[186:189], v[106:109]
	v_mfma_f32_16x16x32_bf16 v[102:105], v[170:173], v[186:189], v[102:105]
	v_mfma_f32_16x16x32_bf16 v[90:93], v[162:165], v[194:197], v[90:93]
	v_mfma_f32_16x16x32_bf16 v[86:89], v[170:173], v[194:197], v[86:89]
	v_mfma_f32_16x16x32_bf16 v[74:77], v[162:165], v[226:229], v[74:77]
	v_mfma_f32_16x16x32_bf16 v[70:73], v[170:173], v[226:229], v[70:73]
	s_setprio 0
	s_barrier
	s_add_i32 s0, s38, s75
	v_lshl_add_u64 v[206:207], v[206:207], 0, s[42:43]
	s_mov_b32 m0, s0
	ds_read_b128 v[174:177], v144 offset:49152
	ds_read_b128 v[178:181], v144 offset:50176
	ds_read_b128 v[182:185], v144 offset:51200
	ds_read_b128 v[186:189], v144 offset:52224
	ds_read_b128 v[190:193], v144 offset:53248
	ds_read_b128 v[194:197], v144 offset:54272
	ds_read_b128 v[198:201], v144 offset:55296
	ds_read_b128 v[226:229], v144 offset:56320
	global_load_lds_dwordx4 v[206:207], off
	s_add_i32 m0, s0, 0x2000
	s_add_u32 s0, s28, 0x80080
	v_lshl_add_u64 v[206:207], v[230:231], 0, s[42:43]
	s_addc_u32 s1, s29, 0
	s_add_i32 s2, s39, s75
	global_load_lds_dwordx4 v[206:207], off
	v_lshl_add_u64 v[206:207], s[0:1], 0, v[202:203]
	s_mov_b32 m0, s2
	s_nop 0
	global_load_lds_dwordx4 v[206:207], off
	v_lshl_add_u64 v[206:207], s[0:1], 0, v[134:135]
	s_add_i32 m0, s2, 0x2000
	s_nop 0
	global_load_lds_dwordx4 v[206:207], off
	s_waitcnt vmcnt(6)
	s_waitcnt lgkmcnt(0)
	s_barrier
	s_setprio 1
	v_mfma_f32_16x16x32_bf16 v[62:65], v[136:139], v[174:177], v[62:65]
	v_mfma_f32_16x16x32_bf16 v[50:53], v[150:153], v[174:177], v[50:53]
	v_mfma_f32_16x16x32_bf16 v[46:49], v[136:139], v[182:185], v[46:49]
	v_mfma_f32_16x16x32_bf16 v[34:37], v[150:153], v[182:185], v[34:37]
	v_mfma_f32_16x16x32_bf16 v[30:33], v[136:139], v[190:193], v[30:33]
	v_mfma_f32_16x16x32_bf16 v[18:21], v[150:153], v[190:193], v[18:21]
	v_mfma_f32_16x16x32_bf16 v[14:17], v[136:139], v[198:201], v[14:17]
	v_mfma_f32_16x16x32_bf16 v[6:9], v[150:153], v[198:201], v[6:9]
	v_mfma_f32_16x16x32_bf16 v[62:65], v[146:149], v[178:181], v[62:65]
	v_mfma_f32_16x16x32_bf16 v[50:53], v[154:157], v[178:181], v[50:53]
	v_mfma_f32_16x16x32_bf16 v[46:49], v[146:149], v[186:189], v[46:49]
	v_mfma_f32_16x16x32_bf16 v[34:37], v[154:157], v[186:189], v[34:37]
	v_mfma_f32_16x16x32_bf16 v[30:33], v[146:149], v[194:197], v[30:33]
	v_mfma_f32_16x16x32_bf16 v[18:21], v[154:157], v[194:197], v[18:21]
	v_mfma_f32_16x16x32_bf16 v[14:17], v[146:149], v[226:229], v[14:17]
	v_mfma_f32_16x16x32_bf16 v[6:9], v[154:157], v[226:229], v[6:9]
	v_mfma_f32_16x16x32_bf16 v[58:61], v[158:161], v[174:177], v[58:61]
	v_mfma_f32_16x16x32_bf16 v[54:57], v[166:169], v[174:177], v[54:57]
	v_mfma_f32_16x16x32_bf16 v[42:45], v[158:161], v[182:185], v[42:45]
	v_mfma_f32_16x16x32_bf16 v[38:41], v[166:169], v[182:185], v[38:41]
	v_mfma_f32_16x16x32_bf16 v[26:29], v[158:161], v[190:193], v[26:29]
	v_mfma_f32_16x16x32_bf16 v[22:25], v[166:169], v[190:193], v[22:25]
	v_mfma_f32_16x16x32_bf16 v[10:13], v[158:161], v[198:201], v[10:13]
	v_mfma_f32_16x16x32_bf16 v[2:5], v[166:169], v[198:201], v[2:5]
	v_mfma_f32_16x16x32_bf16 v[58:61], v[162:165], v[178:181], v[58:61]
	v_mfma_f32_16x16x32_bf16 v[54:57], v[170:173], v[178:181], v[54:57]
	v_mfma_f32_16x16x32_bf16 v[42:45], v[162:165], v[186:189], v[42:45]
	v_mfma_f32_16x16x32_bf16 v[38:41], v[170:173], v[186:189], v[38:41]
	v_mfma_f32_16x16x32_bf16 v[26:29], v[162:165], v[194:197], v[26:29]
	v_mfma_f32_16x16x32_bf16 v[22:25], v[170:173], v[194:197], v[22:25]
	v_mfma_f32_16x16x32_bf16 v[10:13], v[162:165], v[226:229], v[10:13]
	v_mfma_f32_16x16x32_bf16 v[2:5], v[170:173], v[226:229], v[2:5]
	s_setprio 0
	s_barrier
	s_cmp_gt_u32 s88, 29
	s_mov_b32 s88, s22
	s_cbranch_scc1 .LBB0_1061
